# nt cache policy on P1 (Z), P8 (HID) and PLE-proj GEMM epilogue stores
# speedup vs baseline: 1.0193x; 1.0193x over previous
; __device__ __forceinline__ unsigned pk2(float lo, float hi) { f32x2_t v = {lo, hi}; bf16x2_t b = __builtin_convertvector(v, bf16x2_t); return __builtin_bit_cast(unsigned, b); }
;     __device__ __forceinline__ void operator()(const f32x4 (&acc)[2][2][4][2], const pg8::Unit& u, int wr, int wc, int fr, int fq) const {
;         const int row0 = u.pm * 256 + wr * 64 + fr, col0 = u.pn * 256 + wc * 32 + 8 * fq;
; #pragma unroll
;         for (int ai = 0; ai < 2; ++ai)
; #pragma unroll
;             for (int m = 0; m < 4; ++m) { bf16* rowp = O + (size_t)(row0 + ai * 128 + m * 16) * ldc + col0;
; #pragma unroll
;                 for (int bj = 0; bj < 2; ++bj) { const f32x4 v0 = acc[ai][bj][m][0], v1 = acc[ai][bj][m][1];
;                     u32x4 w; w.x = pk2(v0[0], v0[1]); w.y = pk2(v0[2], v0[3]); w.z = pk2(v1[0], v1[1]); w.w = pk2(v1[2], v1[3]);
;                     *(u32x4*)(rowp + bj * 128) = w; } }
.LBB0_181:
	v_lshl_add_u32 v152, s18, 8, v145
	v_lshl_or_b32 v154, s46, 8, v147
	v_ashrrev_i32_e32 v153, 31, v152
	v_ashrrev_i32_e32 v155, 31, v154
	v_lshlrev_b64 v[156:157], 14, v[152:153]
	v_lshl_add_u64 v[156:157], s[72:73], 0, v[156:157]
	v_lshlrev_b64 v[154:155], 1, v[154:155]
	v_lshl_add_u64 v[156:157], v[156:157], 0, v[154:155]
	s_mov_b32 s18, 0x200000
	s_mov_b64 s[28:29], 0x200000
	v_cvt_pk_bf16_f32 v60, v60, v61
	v_cvt_pk_bf16_f32 v61, v62, v63
	v_cvt_pk_bf16_f32 v62, v56, v57
	v_add_co_u32_e32 v56, vcc, s18, v156
	v_cvt_pk_bf16_f32 v68, v68, v69
	v_cvt_pk_bf16_f32 v69, v70, v71
	v_cvt_pk_bf16_f32 v70, v64, v65
	v_lshl_add_u64 v[64:65], v[156:157], 0, s[28:29]
	v_addc_co_u32_e32 v57, vcc, 0, v157, vcc
	v_cvt_pk_bf16_f32 v44, v44, v45
	v_cvt_pk_bf16_f32 v45, v46, v47
	v_cvt_pk_bf16_f32 v46, v40, v41
	v_cvt_pk_bf16_f32 v47, v42, v43
	s_mov_b32 s18, 0x240000
	v_cvt_pk_bf16_f32 v108, v108, v109
	v_cvt_pk_bf16_f32 v109, v110, v111
	v_cvt_pk_bf16_f32 v110, v104, v105
	v_or_b32_e32 v104, 16, v152
	global_store_dwordx4 v[64:65], v[44:47], off offset:256 nt
	s_mov_b64 s[28:29], 0x240000
	v_ashrrev_i32_e32 v105, 31, v104
	v_add_co_u32_e32 v46, vcc, s18, v156
	v_cvt_pk_bf16_f32 v92, v92, v93
	v_cvt_pk_bf16_f32 v93, v94, v95
	v_cvt_pk_bf16_f32 v94, v88, v89
	v_or_b32_e32 v88, 32, v152
	v_lshl_add_u64 v[44:45], v[156:157], 0, s[28:29]
	v_addc_co_u32_e32 v47, vcc, 0, v157, vcc
	v_cvt_pk_bf16_f32 v28, v28, v29
	v_cvt_pk_bf16_f32 v29, v30, v31
	v_cvt_pk_bf16_f32 v30, v24, v25
	v_cvt_pk_bf16_f32 v31, v26, v27
	s_mov_b32 s18, 0x280000
	v_lshlrev_b64 v[104:105], 14, v[104:105]
	v_ashrrev_i32_e32 v89, 31, v88
	v_cvt_pk_bf16_f32 v76, v76, v77
	v_cvt_pk_bf16_f32 v77, v78, v79
	v_cvt_pk_bf16_f32 v78, v72, v73
	v_or_b32_e32 v72, 48, v152
	global_store_dwordx4 v[44:45], v[28:31], off offset:256 nt
	s_mov_b64 s[28:29], 0x280000
	v_cvt_pk_bf16_f32 v111, v106, v107
	v_add_co_u32_e32 v30, vcc, s18, v156
	v_lshl_add_u64 v[104:105], s[72:73], 0, v[104:105]
	v_lshlrev_b64 v[88:89], 14, v[88:89]
	v_ashrrev_i32_e32 v73, 31, v72
	v_lshl_add_u64 v[28:29], v[156:157], 0, s[28:29]
	v_addc_co_u32_e32 v31, vcc, 0, v157, vcc
	v_cvt_pk_bf16_f32 v12, v12, v13
	v_cvt_pk_bf16_f32 v13, v14, v15
	v_cvt_pk_bf16_f32 v14, v8, v9
	v_cvt_pk_bf16_f32 v15, v10, v11
	s_mov_b32 s18, 0x2c0000
	global_store_dwordx4 v[156:157], v[108:111], off offset:256 nt
	v_cvt_pk_bf16_f32 v95, v90, v91
	v_lshl_add_u64 v[88:89], s[72:73], 0, v[88:89]
	v_lshl_add_u64 v[108:109], v[104:105], 0, v[154:155]
	v_lshlrev_b64 v[72:73], 14, v[72:73]
	global_store_dwordx4 v[28:29], v[12:15], off offset:256 nt
	global_store_dwordx4 v[108:109], v[92:95], off offset:256 nt
	v_cvt_pk_bf16_f32 v79, v74, v75
	v_add_co_u32_e32 v14, vcc, s18, v156
	v_lshl_add_u64 v[92:93], v[88:89], 0, v[154:155]
	v_lshl_add_u64 v[72:73], s[72:73], 0, v[72:73]
	s_mov_b64 s[28:29], 0x2c0000
	v_addc_co_u32_e32 v15, vcc, 0, v157, vcc
	v_cvt_pk_bf16_f32 v124, v124, v125
	v_cvt_pk_bf16_f32 v125, v126, v127
	v_cvt_pk_bf16_f32 v126, v120, v121
	v_cvt_pk_bf16_f32 v127, v122, v123
	v_cvt_pk_bf16_f32 v104, v116, v117
	v_cvt_pk_bf16_f32 v105, v118, v119
	v_cvt_pk_bf16_f32 v106, v112, v113
	v_cvt_pk_bf16_f32 v107, v114, v115
	v_cvt_pk_bf16_f32 v88, v100, v101
	v_cvt_pk_bf16_f32 v89, v102, v103
	v_cvt_pk_bf16_f32 v90, v96, v97
	v_cvt_pk_bf16_f32 v91, v98, v99
	global_store_dwordx4 v[92:93], v[76:79], off offset:256 nt
	v_cvt_pk_bf16_f32 v74, v80, v81
	v_cvt_pk_bf16_f32 v75, v82, v83
	v_lshl_add_u64 v[76:77], v[72:73], 0, v[154:155]
	v_cvt_pk_bf16_f32 v72, v84, v85
	v_cvt_pk_bf16_f32 v73, v86, v87
	v_cvt_pk_bf16_f32 v71, v66, v67
	v_cvt_pk_bf16_f32 v63, v58, v59
	v_cvt_pk_bf16_f32 v40, v52, v53
	v_cvt_pk_bf16_f32 v41, v54, v55
	v_cvt_pk_bf16_f32 v42, v48, v49
	v_cvt_pk_bf16_f32 v43, v50, v51
	v_cvt_pk_bf16_f32 v24, v36, v37
	v_cvt_pk_bf16_f32 v25, v38, v39
	v_cvt_pk_bf16_f32 v26, v32, v33
	v_cvt_pk_bf16_f32 v27, v34, v35
	v_lshl_add_u64 v[12:13], v[156:157], 0, s[28:29]
	v_cvt_pk_bf16_f32 v8, v20, v21
	v_cvt_pk_bf16_f32 v9, v22, v23
	v_cvt_pk_bf16_f32 v10, v16, v17
	v_cvt_pk_bf16_f32 v11, v18, v19
	v_cvt_pk_bf16_f32 v4, v4, v5
	v_cvt_pk_bf16_f32 v5, v6, v7
	v_cvt_pk_bf16_f32 v6, v0, v1
	v_cvt_pk_bf16_f32 v7, v2, v3
	s_andn2_b64 vcc, exec, s[0:1]
	s_mov_b64 s[0:1], -1
	global_store_dwordx4 v[156:157], v[124:127], off nt
	global_store_dwordx4 v[108:109], v[104:107], off nt
	global_store_dwordx4 v[92:93], v[88:91], off nt
	global_store_dwordx4 v[76:77], v[72:75], off nt
	global_store_dwordx4 v[76:77], v[68:71], off offset:256 nt
	global_store_dwordx4 v[56:57], v[60:63], off nt
	global_store_dwordx4 v[46:47], v[40:43], off nt
	global_store_dwordx4 v[30:31], v[24:27], off nt
	global_store_dwordx4 v[14:15], v[8:11], off nt
	global_store_dwordx4 v[12:13], v[4:7], off offset:256 nt
	s_cbranch_vccnz .LBB0_170
	s_andn2_b64 vcc, exec, s[4:5]
	s_cbranch_vccnz .LBB0_169
	s_barrier
	s_branch .LBB0_169

; __device__ __forceinline__ float siluf(float x) { return x * sigm(x); }
; __device__ __forceinline__ u32x4 pack8(const float (&v)[8]) { u32x4 w; w.x = pk2(v[0], v[1]); w.y = pk2(v[2], v[3]); w.z = pk2(v[4], v[5]); w.w = pk2(v[6], v[7]); return w; }
;     __device__ __forceinline__ void operator()(const f32x4 (&acc)[2][2][4][2], const pg8::Unit& u, int wr, int wc, int fr, int fq) const {
;         const int row0 = u.pm * 256 + wr * 64 + fr, col0 = u.pn * 128 + wc * 32 + 8 * fq;
; #pragma unroll
;         for (int ai = 0; ai < 2; ++ai)
; #pragma unroll
;             for (int m = 0; m < 4; ++m) { const size_t row = (size_t)(row0 + ai * 128 + m * 16);
;                 const f32x4 g0 = acc[ai][0][m][0], g1 = acc[ai][0][m][1], u0 = acc[ai][1][m][0], u1 = acc[ai][1][m][1];
;                 float o[8];
; #pragma unroll
;                 for (int e = 0; e < 4; ++e) { o[e] = siluf(g0[e]) * u0[e]; o[4 + e] = siluf(g1[e]) * u1[e]; }
;                 *(u32x4*)(Hd + row * FF + col0) = pack8(o); }
;     }
.LBB0_978:
	v_mul_f32_e32 v161, 0xbfb8aa3b, v124
	v_mul_f32_e32 v166, 0xbfb8aa3b, v120
	v_exp_f32_e32 v161, v161
	v_exp_f32_e32 v167, v166
	v_mul_f32_e32 v166, 0xbfb8aa3b, v125
	v_exp_f32_e32 v168, v166
	v_add_f32_e32 v161, 1.0, v161
	v_rcp_f32_e32 v166, v161
	v_add_f32_e32 v161, 1.0, v167
	v_add_f32_e32 v167, 1.0, v168
	v_rcp_f32_e32 v167, v167
	v_mul_f32_e32 v168, 0xbfb8aa3b, v121
	v_exp_f32_e32 v169, v168
	v_rcp_f32_e32 v168, v161
	v_pk_mul_f32 v[124:125], v[124:125], v[166:167]
	v_mul_f32_e32 v161, 0xbfb8aa3b, v127
	v_pk_mul_f32 v[116:117], v[124:125], v[116:117]
	v_add_f32_e32 v124, 1.0, v169
	v_mul_f32_e32 v125, 0xbfb8aa3b, v122
	v_rcp_f32_e32 v169, v124
	v_mul_f32_e32 v124, 0xbfb8aa3b, v126
	v_exp_f32_e32 v125, v125
	v_exp_f32_e32 v124, v124
	v_exp_f32_e32 v161, v161
	v_mul_f32_e32 v166, 0xbfb8aa3b, v123
	v_exp_f32_e32 v167, v166
	v_add_f32_e32 v125, 1.0, v125
	v_add_f32_e32 v124, 1.0, v124
	v_rcp_f32_e32 v166, v125
	v_add_f32_e32 v125, 1.0, v161
	v_rcp_f32_e32 v124, v124
	v_rcp_f32_e32 v125, v125
	v_add_f32_e32 v161, 1.0, v167
	v_rcp_f32_e32 v167, v161
	v_pk_mul_f32 v[120:121], v[120:121], v[168:169]
	v_lshl_or_b32 v164, s50, 7, v156
	v_pk_mul_f32 v[112:113], v[120:121], v[112:113]
	v_pk_mul_f32 v[120:121], v[126:127], v[124:125]
	v_lshl_add_u32 v160, s26, 8, v153
	v_pk_mul_f32 v[118:119], v[120:121], v[118:119]
	v_pk_mul_f32 v[120:121], v[122:123], v[166:167]
	v_ashrrev_i32_e32 v165, 31, v164
	v_pk_mul_f32 v[114:115], v[120:121], v[114:115]
	v_cvt_pk_bf16_f32 v116, v116, v117
	v_cvt_pk_bf16_f32 v117, v118, v119
	v_cvt_pk_bf16_f32 v118, v112, v113
	v_mov_b64_e32 v[112:113], s[72:73]
	v_cvt_pk_bf16_f32 v119, v114, v115
	v_mad_i64_i32 v[120:121], s[28:29], v160, s49, v[112:113]
	v_lshlrev_b64 v[114:115], 1, v[164:165]
	v_lshl_add_u64 v[120:121], v[120:121], 0, v[114:115]
	global_store_dwordx4 v[120:121], v[116:119], off nt
	v_or_b32_e32 v120, 16, v160
	s_andn2_b64 vcc, exec, s[0:1]
	v_mul_f32_e32 v116, 0xbfb8aa3b, v108
	v_mul_f32_e32 v117, 0xbfb8aa3b, v104
	v_mul_f32_e32 v118, 0xbfb8aa3b, v109
	v_exp_f32_e32 v116, v116
	v_exp_f32_e32 v117, v117
	v_exp_f32_e32 v118, v118
	s_mov_b64 s[0:1], -1
	v_add_f32_e32 v116, 1.0, v116
	v_add_f32_e32 v119, 1.0, v117
	v_add_f32_e32 v117, 1.0, v118
	v_rcp_f32_e32 v116, v116
	v_rcp_f32_e32 v117, v117
	v_mul_f32_e32 v118, 0xbfb8aa3b, v105
	v_exp_f32_e32 v121, v118
	v_rcp_f32_e32 v118, v119
	v_pk_mul_f32 v[108:109], v[108:109], v[116:117]
	v_mul_f32_e32 v116, 0xbfb8aa3b, v111
	v_pk_mul_f32 v[100:101], v[108:109], v[100:101]
	v_add_f32_e32 v108, 1.0, v121
	v_rcp_f32_e32 v119, v108
	v_mul_f32_e32 v109, 0xbfb8aa3b, v106
	v_mul_f32_e32 v108, 0xbfb8aa3b, v110
	v_exp_f32_e32 v109, v109
	v_exp_f32_e32 v108, v108
	v_exp_f32_e32 v117, v116
	v_mul_f32_e32 v116, 0xbfb8aa3b, v107
	v_pk_mul_f32 v[104:105], v[104:105], v[118:119]
	v_exp_f32_e32 v118, v116
	v_add_f32_e32 v109, 1.0, v109
	v_add_f32_e32 v108, 1.0, v108
	v_rcp_f32_e32 v116, v109
	v_add_f32_e32 v109, 1.0, v117
	v_rcp_f32_e32 v108, v108
	v_rcp_f32_e32 v109, v109
	v_add_f32_e32 v117, 1.0, v118
	v_rcp_f32_e32 v117, v117
	v_pk_mul_f32 v[104:105], v[104:105], v[96:97]
	v_pk_mul_f32 v[96:97], v[110:111], v[108:109]
	s_nop 0
	v_pk_mul_f32 v[102:103], v[96:97], v[102:103]
	v_pk_mul_f32 v[96:97], v[106:107], v[116:117]
	s_nop 0
	v_pk_mul_f32 v[106:107], v[96:97], v[98:99]
	v_cvt_pk_bf16_f32 v96, v100, v101
	v_mad_i64_i32 v[100:101], s[28:29], v120, s49, v[112:113]
	v_cvt_pk_bf16_f32 v97, v102, v103
	v_cvt_pk_bf16_f32 v98, v104, v105
	v_cvt_pk_bf16_f32 v99, v106, v107
	v_lshl_add_u64 v[100:101], v[100:101], 0, v[114:115]
	global_store_dwordx4 v[100:101], v[96:99], off nt
	v_or_b32_e32 v100, 32, v160
	s_nop 0
	v_mul_f32_e32 v96, 0xbfb8aa3b, v92
	v_mul_f32_e32 v97, 0xbfb8aa3b, v88
	v_mul_f32_e32 v98, 0xbfb8aa3b, v93
	v_exp_f32_e32 v96, v96
	v_exp_f32_e32 v97, v97
	v_exp_f32_e32 v98, v98
	v_add_f32_e32 v96, 1.0, v96
	v_add_f32_e32 v99, 1.0, v97
	v_add_f32_e32 v97, 1.0, v98
	v_rcp_f32_e32 v96, v96
	v_rcp_f32_e32 v97, v97
	v_mul_f32_e32 v98, 0xbfb8aa3b, v89
	v_exp_f32_e32 v101, v98
	v_rcp_f32_e32 v98, v99
	v_pk_mul_f32 v[92:93], v[92:93], v[96:97]
	v_mul_f32_e32 v96, 0xbfb8aa3b, v95
	v_pk_mul_f32 v[84:85], v[92:93], v[84:85]
	v_add_f32_e32 v92, 1.0, v101
	v_rcp_f32_e32 v99, v92
	v_mul_f32_e32 v93, 0xbfb8aa3b, v90
	v_mul_f32_e32 v92, 0xbfb8aa3b, v94
	v_exp_f32_e32 v93, v93
	v_exp_f32_e32 v92, v92
	v_exp_f32_e32 v97, v96
	v_mul_f32_e32 v96, 0xbfb8aa3b, v91
	v_pk_mul_f32 v[88:89], v[88:89], v[98:99]
	v_exp_f32_e32 v98, v96
	v_add_f32_e32 v93, 1.0, v93
	v_add_f32_e32 v92, 1.0, v92
	v_rcp_f32_e32 v96, v93
	v_add_f32_e32 v93, 1.0, v97
	v_rcp_f32_e32 v92, v92
	v_rcp_f32_e32 v93, v93
	v_add_f32_e32 v97, 1.0, v98
	v_rcp_f32_e32 v97, v97
	v_pk_mul_f32 v[88:89], v[88:89], v[80:81]
	v_pk_mul_f32 v[80:81], v[94:95], v[92:93]
	s_nop 0
	v_pk_mul_f32 v[86:87], v[80:81], v[86:87]
	v_pk_mul_f32 v[80:81], v[90:91], v[96:97]
	s_nop 0
	v_pk_mul_f32 v[90:91], v[80:81], v[82:83]
	v_cvt_pk_bf16_f32 v80, v84, v85
	v_mad_i64_i32 v[84:85], s[28:29], v100, s49, v[112:113]
	v_cvt_pk_bf16_f32 v81, v86, v87
	v_cvt_pk_bf16_f32 v82, v88, v89
	v_cvt_pk_bf16_f32 v83, v90, v91
	v_lshl_add_u64 v[84:85], v[84:85], 0, v[114:115]
	global_store_dwordx4 v[84:85], v[80:83], off nt
	v_or_b32_e32 v84, 48, v160
	s_nop 0
	v_mul_f32_e32 v80, 0xbfb8aa3b, v76
	v_mul_f32_e32 v81, 0xbfb8aa3b, v72
	v_mul_f32_e32 v82, 0xbfb8aa3b, v77
	v_exp_f32_e32 v80, v80
	v_exp_f32_e32 v81, v81
	v_exp_f32_e32 v82, v82
	v_add_f32_e32 v80, 1.0, v80
	v_add_f32_e32 v83, 1.0, v81
	v_add_f32_e32 v81, 1.0, v82
	v_rcp_f32_e32 v80, v80
	v_rcp_f32_e32 v81, v81
	v_mul_f32_e32 v82, 0xbfb8aa3b, v73
	v_exp_f32_e32 v85, v82
	v_rcp_f32_e32 v82, v83
; __device__ __forceinline__ float siluf(float x) { return x * sigm(x); }
; __device__ __forceinline__ u32x4 pack8(const float (&v)[8]) { u32x4 w; w.x = pk2(v[0], v[1]); w.y = pk2(v[2], v[3]); w.z = pk2(v[4], v[5]); w.w = pk2(v[6], v[7]); return w; }
;     __device__ __forceinline__ void operator()(const f32x4 (&acc)[2][2][4][2], const pg8::Unit& u, int wr, int wc, int fr, int fq) const {
;         const int row0 = u.pm * 256 + wr * 64 + fr, col0 = u.pn * 128 + wc * 32 + 8 * fq;
; #pragma unroll
;         for (int ai = 0; ai < 2; ++ai)
; #pragma unroll
;             for (int m = 0; m < 4; ++m) { const size_t row = (size_t)(row0 + ai * 128 + m * 16);
;                 const f32x4 g0 = acc[ai][0][m][0], g1 = acc[ai][0][m][1], u0 = acc[ai][1][m][0], u1 = acc[ai][1][m][1];
;                 float o[8];
; #pragma unroll
;                 for (int e = 0; e < 4; ++e) { o[e] = siluf(g0[e]) * u0[e]; o[4 + e] = siluf(g1[e]) * u1[e]; }
;                 *(u32x4*)(Hd + row * FF + col0) = pack8(o); }
;     }
	v_pk_mul_f32 v[76:77], v[76:77], v[80:81]
	v_mul_f32_e32 v80, 0xbfb8aa3b, v79
	v_pk_mul_f32 v[68:69], v[76:77], v[68:69]
	v_add_f32_e32 v76, 1.0, v85
	v_rcp_f32_e32 v83, v76
	v_mul_f32_e32 v77, 0xbfb8aa3b, v74
	v_mul_f32_e32 v76, 0xbfb8aa3b, v78
	v_exp_f32_e32 v77, v77
	v_exp_f32_e32 v76, v76
	v_exp_f32_e32 v81, v80
	v_mul_f32_e32 v80, 0xbfb8aa3b, v75
	v_pk_mul_f32 v[72:73], v[72:73], v[82:83]
	v_exp_f32_e32 v82, v80
	v_add_f32_e32 v77, 1.0, v77
	v_add_f32_e32 v76, 1.0, v76
	v_rcp_f32_e32 v80, v77
	v_add_f32_e32 v77, 1.0, v81
	v_rcp_f32_e32 v76, v76
	v_rcp_f32_e32 v77, v77
	v_add_f32_e32 v81, 1.0, v82
	v_rcp_f32_e32 v81, v81
	v_pk_mul_f32 v[72:73], v[72:73], v[64:65]
	v_pk_mul_f32 v[64:65], v[78:79], v[76:77]
	s_nop 0
	v_pk_mul_f32 v[70:71], v[64:65], v[70:71]
	v_pk_mul_f32 v[64:65], v[74:75], v[80:81]
	s_nop 0
	v_pk_mul_f32 v[74:75], v[64:65], v[66:67]
	v_cvt_pk_bf16_f32 v64, v68, v69
	v_mad_i64_i32 v[68:69], s[28:29], v84, s49, v[112:113]
	v_cvt_pk_bf16_f32 v65, v70, v71
	v_cvt_pk_bf16_f32 v66, v72, v73
	v_cvt_pk_bf16_f32 v67, v74, v75
	v_lshl_add_u64 v[68:69], v[68:69], 0, v[114:115]
	global_store_dwordx4 v[68:69], v[64:67], off nt
	v_add_u32_e32 v68, 0x80, v160
	s_nop 0
	v_mul_f32_e32 v64, 0xbfb8aa3b, v60
	v_mul_f32_e32 v65, 0xbfb8aa3b, v56
	v_mul_f32_e32 v66, 0xbfb8aa3b, v61
	v_exp_f32_e32 v64, v64
	v_exp_f32_e32 v65, v65
	v_exp_f32_e32 v66, v66
	v_add_f32_e32 v64, 1.0, v64
	v_add_f32_e32 v67, 1.0, v65
	v_add_f32_e32 v65, 1.0, v66
	v_rcp_f32_e32 v64, v64
	v_rcp_f32_e32 v65, v65
	v_mul_f32_e32 v66, 0xbfb8aa3b, v57
	v_exp_f32_e32 v69, v66
	v_rcp_f32_e32 v66, v67
	v_pk_mul_f32 v[60:61], v[60:61], v[64:65]
	v_mul_f32_e32 v64, 0xbfb8aa3b, v63
	v_pk_mul_f32 v[52:53], v[60:61], v[52:53]
	v_add_f32_e32 v60, 1.0, v69
	v_rcp_f32_e32 v67, v60
	v_mul_f32_e32 v61, 0xbfb8aa3b, v58
	v_mul_f32_e32 v60, 0xbfb8aa3b, v62
	v_exp_f32_e32 v61, v61
	v_exp_f32_e32 v60, v60
	v_exp_f32_e32 v65, v64
	v_mul_f32_e32 v64, 0xbfb8aa3b, v59
	v_pk_mul_f32 v[56:57], v[56:57], v[66:67]
	v_exp_f32_e32 v66, v64
	v_add_f32_e32 v61, 1.0, v61
	v_add_f32_e32 v60, 1.0, v60
	v_rcp_f32_e32 v64, v61
	v_add_f32_e32 v61, 1.0, v65
	v_rcp_f32_e32 v60, v60
	v_rcp_f32_e32 v61, v61
	v_add_f32_e32 v65, 1.0, v66
	v_rcp_f32_e32 v65, v65
	v_pk_mul_f32 v[56:57], v[56:57], v[48:49]
	v_pk_mul_f32 v[48:49], v[62:63], v[60:61]
	s_nop 0
	v_pk_mul_f32 v[54:55], v[48:49], v[54:55]
	v_pk_mul_f32 v[48:49], v[58:59], v[64:65]
	s_nop 0
	v_pk_mul_f32 v[58:59], v[48:49], v[50:51]
	v_cvt_pk_bf16_f32 v48, v52, v53
	v_mad_i64_i32 v[52:53], s[28:29], v68, s49, v[112:113]
	v_cvt_pk_bf16_f32 v49, v54, v55
	v_cvt_pk_bf16_f32 v50, v56, v57
	v_cvt_pk_bf16_f32 v51, v58, v59
	v_lshl_add_u64 v[52:53], v[52:53], 0, v[114:115]
	global_store_dwordx4 v[52:53], v[48:51], off nt
	v_add_u32_e32 v52, 0x90, v160
	s_nop 0
	v_mul_f32_e32 v48, 0xbfb8aa3b, v44
	v_mul_f32_e32 v49, 0xbfb8aa3b, v40
	v_mul_f32_e32 v50, 0xbfb8aa3b, v45
	v_exp_f32_e32 v48, v48
	v_exp_f32_e32 v49, v49
	v_exp_f32_e32 v50, v50
	v_add_f32_e32 v48, 1.0, v48
	v_add_f32_e32 v51, 1.0, v49
	v_add_f32_e32 v49, 1.0, v50
	v_rcp_f32_e32 v48, v48
	v_rcp_f32_e32 v49, v49
	v_mul_f32_e32 v50, 0xbfb8aa3b, v41
	v_exp_f32_e32 v53, v50
	v_rcp_f32_e32 v50, v51
	v_pk_mul_f32 v[44:45], v[44:45], v[48:49]
	v_mul_f32_e32 v48, 0xbfb8aa3b, v47
	v_pk_mul_f32 v[36:37], v[44:45], v[36:37]
	v_add_f32_e32 v44, 1.0, v53
	v_rcp_f32_e32 v51, v44
	v_mul_f32_e32 v45, 0xbfb8aa3b, v42
	v_mul_f32_e32 v44, 0xbfb8aa3b, v46
	v_exp_f32_e32 v45, v45
	v_exp_f32_e32 v44, v44
	v_exp_f32_e32 v49, v48
	v_mul_f32_e32 v48, 0xbfb8aa3b, v43
	v_pk_mul_f32 v[40:41], v[40:41], v[50:51]
	v_exp_f32_e32 v50, v48
	v_add_f32_e32 v45, 1.0, v45
	v_add_f32_e32 v44, 1.0, v44
	v_rcp_f32_e32 v48, v45
	v_add_f32_e32 v45, 1.0, v49
	v_rcp_f32_e32 v44, v44
	v_rcp_f32_e32 v45, v45
	v_add_f32_e32 v49, 1.0, v50
; __device__ __forceinline__ float siluf(float x) { return x * sigm(x); }
; __device__ __forceinline__ u32x4 pack8(const float (&v)[8]) { u32x4 w; w.x = pk2(v[0], v[1]); w.y = pk2(v[2], v[3]); w.z = pk2(v[4], v[5]); w.w = pk2(v[6], v[7]); return w; }
;     __device__ __forceinline__ void operator()(const f32x4 (&acc)[2][2][4][2], const pg8::Unit& u, int wr, int wc, int fr, int fq) const {
;         const int row0 = u.pm * 256 + wr * 64 + fr, col0 = u.pn * 128 + wc * 32 + 8 * fq;
; #pragma unroll
;         for (int ai = 0; ai < 2; ++ai)
; #pragma unroll
;             for (int m = 0; m < 4; ++m) { const size_t row = (size_t)(row0 + ai * 128 + m * 16);
;                 const f32x4 g0 = acc[ai][0][m][0], g1 = acc[ai][0][m][1], u0 = acc[ai][1][m][0], u1 = acc[ai][1][m][1];
;                 float o[8];
; #pragma unroll
;                 for (int e = 0; e < 4; ++e) { o[e] = siluf(g0[e]) * u0[e]; o[4 + e] = siluf(g1[e]) * u1[e]; }
;                 *(u32x4*)(Hd + row * FF + col0) = pack8(o); }
;     }
	v_rcp_f32_e32 v49, v49
	v_pk_mul_f32 v[40:41], v[40:41], v[32:33]
	v_pk_mul_f32 v[32:33], v[46:47], v[44:45]
	s_nop 0
	v_pk_mul_f32 v[38:39], v[32:33], v[38:39]
	v_pk_mul_f32 v[32:33], v[42:43], v[48:49]
	s_nop 0
	v_pk_mul_f32 v[42:43], v[32:33], v[34:35]
	v_cvt_pk_bf16_f32 v32, v36, v37
	v_mad_i64_i32 v[36:37], s[28:29], v52, s49, v[112:113]
	v_cvt_pk_bf16_f32 v33, v38, v39
	v_cvt_pk_bf16_f32 v34, v40, v41
	v_cvt_pk_bf16_f32 v35, v42, v43
	v_lshl_add_u64 v[36:37], v[36:37], 0, v[114:115]
	global_store_dwordx4 v[36:37], v[32:35], off nt
	v_add_u32_e32 v36, 0xa0, v160
	s_nop 0
	v_mul_f32_e32 v32, 0xbfb8aa3b, v28
	v_mul_f32_e32 v33, 0xbfb8aa3b, v24
	v_mul_f32_e32 v34, 0xbfb8aa3b, v29
	v_exp_f32_e32 v32, v32
	v_exp_f32_e32 v33, v33
	v_exp_f32_e32 v34, v34
	v_add_f32_e32 v32, 1.0, v32
	v_add_f32_e32 v35, 1.0, v33
	v_add_f32_e32 v33, 1.0, v34
	v_rcp_f32_e32 v32, v32
	v_rcp_f32_e32 v33, v33
	v_mul_f32_e32 v34, 0xbfb8aa3b, v25
	v_exp_f32_e32 v37, v34
	v_rcp_f32_e32 v34, v35
	v_pk_mul_f32 v[28:29], v[28:29], v[32:33]
	v_mul_f32_e32 v32, 0xbfb8aa3b, v31
	v_pk_mul_f32 v[20:21], v[28:29], v[20:21]
	v_add_f32_e32 v28, 1.0, v37
	v_rcp_f32_e32 v35, v28
	v_mul_f32_e32 v29, 0xbfb8aa3b, v26
	v_mul_f32_e32 v28, 0xbfb8aa3b, v30
	v_exp_f32_e32 v29, v29
	v_exp_f32_e32 v28, v28
	v_exp_f32_e32 v33, v32
	v_mul_f32_e32 v32, 0xbfb8aa3b, v27
	v_pk_mul_f32 v[24:25], v[24:25], v[34:35]
	v_exp_f32_e32 v34, v32
	v_add_f32_e32 v29, 1.0, v29
	v_add_f32_e32 v28, 1.0, v28
	v_rcp_f32_e32 v32, v29
	v_add_f32_e32 v29, 1.0, v33
	v_rcp_f32_e32 v28, v28
	v_rcp_f32_e32 v29, v29
	v_add_f32_e32 v33, 1.0, v34
	v_rcp_f32_e32 v33, v33
	v_pk_mul_f32 v[24:25], v[24:25], v[16:17]
	v_pk_mul_f32 v[16:17], v[30:31], v[28:29]
	s_nop 0
	v_pk_mul_f32 v[22:23], v[16:17], v[22:23]
	v_pk_mul_f32 v[16:17], v[26:27], v[32:33]
	s_nop 0
	v_pk_mul_f32 v[26:27], v[16:17], v[18:19]
	v_cvt_pk_bf16_f32 v16, v20, v21
	v_mad_i64_i32 v[20:21], s[28:29], v36, s49, v[112:113]
	v_cvt_pk_bf16_f32 v17, v22, v23
	v_cvt_pk_bf16_f32 v18, v24, v25
	v_cvt_pk_bf16_f32 v19, v26, v27
	v_lshl_add_u64 v[20:21], v[20:21], 0, v[114:115]
	global_store_dwordx4 v[20:21], v[16:19], off nt
	v_add_u32_e32 v20, 0xb0, v160
	s_nop 0
	v_mul_f32_e32 v16, 0xbfb8aa3b, v12
	v_mul_f32_e32 v17, 0xbfb8aa3b, v8
	v_mul_f32_e32 v18, 0xbfb8aa3b, v13
	v_exp_f32_e32 v16, v16
	v_exp_f32_e32 v17, v17
	v_exp_f32_e32 v18, v18
	v_add_f32_e32 v16, 1.0, v16
	v_add_f32_e32 v19, 1.0, v17
	v_add_f32_e32 v17, 1.0, v18
	v_rcp_f32_e32 v16, v16
	v_rcp_f32_e32 v17, v17
	v_mul_f32_e32 v18, 0xbfb8aa3b, v9
	v_exp_f32_e32 v21, v18
	v_rcp_f32_e32 v18, v19
	v_pk_mul_f32 v[12:13], v[12:13], v[16:17]
	v_mul_f32_e32 v16, 0xbfb8aa3b, v15
	v_pk_mul_f32 v[4:5], v[12:13], v[4:5]
	v_add_f32_e32 v12, 1.0, v21
	v_rcp_f32_e32 v19, v12
	v_mul_f32_e32 v13, 0xbfb8aa3b, v10
	v_mul_f32_e32 v12, 0xbfb8aa3b, v14
	v_exp_f32_e32 v13, v13
	v_exp_f32_e32 v12, v12
	v_exp_f32_e32 v17, v16
	v_mul_f32_e32 v16, 0xbfb8aa3b, v11
	v_pk_mul_f32 v[8:9], v[8:9], v[18:19]
	v_exp_f32_e32 v18, v16
	v_add_f32_e32 v13, 1.0, v13
	v_add_f32_e32 v12, 1.0, v12
	v_rcp_f32_e32 v16, v13
	v_add_f32_e32 v13, 1.0, v17
	v_rcp_f32_e32 v12, v12
	v_rcp_f32_e32 v13, v13
	v_add_f32_e32 v17, 1.0, v18
	v_rcp_f32_e32 v17, v17
	v_pk_mul_f32 v[8:9], v[8:9], v[0:1]
	v_pk_mul_f32 v[0:1], v[14:15], v[12:13]
	s_nop 0
	v_pk_mul_f32 v[6:7], v[0:1], v[6:7]
	v_pk_mul_f32 v[0:1], v[10:11], v[16:17]
	s_nop 0
	v_pk_mul_f32 v[10:11], v[0:1], v[2:3]
	v_cvt_pk_bf16_f32 v0, v4, v5
	v_mad_i64_i32 v[4:5], s[28:29], v20, s49, v[112:113]
	v_cvt_pk_bf16_f32 v1, v6, v7
	v_cvt_pk_bf16_f32 v2, v8, v9
	v_cvt_pk_bf16_f32 v3, v10, v11
	v_lshl_add_u64 v[4:5], v[4:5], 0, v[114:115]
	global_store_dwordx4 v[4:5], v[0:3], off nt
	s_cbranch_vccnz .LBB0_971
	s_andn2_b64 vcc, exec, s[6:7]
	s_cbranch_vccnz .LBB0_970
	s_barrier
	s_branch .LBB0_970

; __device__ __forceinline__ unsigned pk2(float lo, float hi) { f32x2_t v = {lo, hi}; bf16x2_t b = __builtin_convertvector(v, bf16x2_t); return __builtin_bit_cast(unsigned, b); }
;     __device__ __forceinline__ void operator()(const f32x4 (&acc)[2][2][4][2], const pg8::Unit& u, int wr, int wc, int fr, int fq) const {
;         const int row0 = u.pm * 256 + wr * 64 + fr, col0 = u.pn * 256 + wc * 32 + 8 * fq;
; #pragma unroll
;         for (int ai = 0; ai < 2; ++ai)
; #pragma unroll
;             for (int m = 0; m < 4; ++m) { bf16* rowp = O + (size_t)(row0 + ai * 128 + m * 16) * ldc + col0;
; #pragma unroll
;                 for (int bj = 0; bj < 2; ++bj) { const f32x4 v0 = acc[ai][bj][m][0], v1 = acc[ai][bj][m][1];
;                     u32x4 w; w.x = pk2(v0[0], v0[1]); w.y = pk2(v0[2], v0[3]); w.z = pk2(v1[0], v1[1]); w.w = pk2(v1[2], v1[3]);
;                     *(u32x4*)(rowp + bj * 128) = w; } }
.LBB0_1007:
	v_lshl_add_u32 v146, s22, 8, v140
	v_lshl_or_b32 v148, s64, 8, v142
	v_ashrrev_i32_e32 v147, 31, v146
	v_ashrrev_i32_e32 v149, 31, v148
	v_lshlrev_b64 v[150:151], 11, v[146:147]
	v_lshl_add_u64 v[150:151], s[68:69], 0, v[150:151]
	v_lshlrev_b64 v[148:149], 1, v[148:149]
	v_lshl_add_u64 v[150:151], v[150:151], 0, v[148:149]
	s_mov_b32 s19, 0x40000
	s_mov_b64 s[24:25], 0x40000
	v_cvt_pk_bf16_f32 v60, v60, v61
	v_cvt_pk_bf16_f32 v61, v62, v63
	v_cvt_pk_bf16_f32 v62, v56, v57
	v_add_co_u32_e32 v56, vcc, s19, v150
	v_cvt_pk_bf16_f32 v68, v68, v69
	v_cvt_pk_bf16_f32 v69, v70, v71
	v_cvt_pk_bf16_f32 v70, v64, v65
	v_lshl_add_u64 v[64:65], v[150:151], 0, s[24:25]
	v_addc_co_u32_e32 v57, vcc, 0, v151, vcc
	v_cvt_pk_bf16_f32 v44, v44, v45
	v_cvt_pk_bf16_f32 v45, v46, v47
	v_cvt_pk_bf16_f32 v46, v40, v41
	v_cvt_pk_bf16_f32 v47, v42, v43
	s_mov_b32 s19, 0x48000
	v_cvt_pk_bf16_f32 v108, v108, v109
	v_cvt_pk_bf16_f32 v109, v110, v111
	v_cvt_pk_bf16_f32 v110, v104, v105
	v_or_b32_e32 v104, 16, v146
	global_store_dwordx4 v[64:65], v[44:47], off offset:256
	s_mov_b64 s[24:25], 0x48000
	v_ashrrev_i32_e32 v105, 31, v104
	v_add_co_u32_e32 v46, vcc, s19, v150
	v_cvt_pk_bf16_f32 v92, v92, v93
	v_cvt_pk_bf16_f32 v93, v94, v95
	v_cvt_pk_bf16_f32 v94, v88, v89
	v_or_b32_e32 v88, 32, v146
	v_lshl_add_u64 v[44:45], v[150:151], 0, s[24:25]
	v_addc_co_u32_e32 v47, vcc, 0, v151, vcc
	v_cvt_pk_bf16_f32 v28, v28, v29
	v_cvt_pk_bf16_f32 v29, v30, v31
	v_cvt_pk_bf16_f32 v30, v24, v25
	v_cvt_pk_bf16_f32 v31, v26, v27
	s_mov_b32 s19, 0x50000
	v_lshlrev_b64 v[104:105], 11, v[104:105]
	v_ashrrev_i32_e32 v89, 31, v88
	v_cvt_pk_bf16_f32 v76, v76, v77
	v_cvt_pk_bf16_f32 v77, v78, v79
	v_cvt_pk_bf16_f32 v78, v72, v73
	v_or_b32_e32 v72, 48, v146
	global_store_dwordx4 v[44:45], v[28:31], off offset:256
	s_mov_b64 s[24:25], 0x50000
	v_cvt_pk_bf16_f32 v111, v106, v107
	v_add_co_u32_e32 v30, vcc, s19, v150
	v_lshl_add_u64 v[104:105], s[68:69], 0, v[104:105]
	v_lshlrev_b64 v[88:89], 11, v[88:89]
	v_ashrrev_i32_e32 v73, 31, v72
	v_lshl_add_u64 v[28:29], v[150:151], 0, s[24:25]
	v_addc_co_u32_e32 v31, vcc, 0, v151, vcc
	v_cvt_pk_bf16_f32 v12, v12, v13
	v_cvt_pk_bf16_f32 v13, v14, v15
	v_cvt_pk_bf16_f32 v14, v8, v9
	v_cvt_pk_bf16_f32 v15, v10, v11
	s_mov_b32 s19, 0x58000
	global_store_dwordx4 v[150:151], v[108:111], off offset:256 nt
	v_cvt_pk_bf16_f32 v95, v90, v91
	v_lshl_add_u64 v[88:89], s[68:69], 0, v[88:89]
	v_lshl_add_u64 v[108:109], v[104:105], 0, v[148:149]
	v_lshlrev_b64 v[72:73], 11, v[72:73]
	global_store_dwordx4 v[28:29], v[12:15], off offset:256 nt
	global_store_dwordx4 v[108:109], v[92:95], off offset:256 nt
	v_cvt_pk_bf16_f32 v79, v74, v75
	v_add_co_u32_e32 v14, vcc, s19, v150
	v_lshl_add_u64 v[92:93], v[88:89], 0, v[148:149]
	v_lshl_add_u64 v[72:73], s[68:69], 0, v[72:73]
	s_mov_b64 s[24:25], 0x58000
	v_addc_co_u32_e32 v15, vcc, 0, v151, vcc
	v_cvt_pk_bf16_f32 v124, v124, v125
	v_cvt_pk_bf16_f32 v125, v126, v127
	v_cvt_pk_bf16_f32 v126, v120, v121
	v_cvt_pk_bf16_f32 v127, v122, v123
	v_cvt_pk_bf16_f32 v104, v116, v117
	v_cvt_pk_bf16_f32 v105, v118, v119
	v_cvt_pk_bf16_f32 v106, v112, v113
	v_cvt_pk_bf16_f32 v107, v114, v115
	v_cvt_pk_bf16_f32 v88, v100, v101
	v_cvt_pk_bf16_f32 v89, v102, v103
	v_cvt_pk_bf16_f32 v90, v96, v97
	v_cvt_pk_bf16_f32 v91, v98, v99
	global_store_dwordx4 v[92:93], v[76:79], off offset:256 nt
	v_cvt_pk_bf16_f32 v74, v80, v81
	v_cvt_pk_bf16_f32 v75, v82, v83
	v_lshl_add_u64 v[76:77], v[72:73], 0, v[148:149]
	v_cvt_pk_bf16_f32 v72, v84, v85
	v_cvt_pk_bf16_f32 v73, v86, v87
	v_cvt_pk_bf16_f32 v71, v66, v67
	v_cvt_pk_bf16_f32 v63, v58, v59
	v_cvt_pk_bf16_f32 v40, v52, v53
	v_cvt_pk_bf16_f32 v41, v54, v55
	v_cvt_pk_bf16_f32 v42, v48, v49
	v_cvt_pk_bf16_f32 v43, v50, v51
	v_cvt_pk_bf16_f32 v24, v36, v37
	v_cvt_pk_bf16_f32 v25, v38, v39
	v_cvt_pk_bf16_f32 v26, v32, v33
	v_cvt_pk_bf16_f32 v27, v34, v35
	v_lshl_add_u64 v[12:13], v[150:151], 0, s[24:25]
	v_cvt_pk_bf16_f32 v8, v20, v21
	v_cvt_pk_bf16_f32 v9, v22, v23
	v_cvt_pk_bf16_f32 v10, v16, v17
	v_cvt_pk_bf16_f32 v11, v18, v19
	v_cvt_pk_bf16_f32 v4, v4, v5
	v_cvt_pk_bf16_f32 v5, v6, v7
	v_cvt_pk_bf16_f32 v6, v0, v1
	v_cvt_pk_bf16_f32 v7, v2, v3
	s_andn2_b64 vcc, exec, s[0:1]
	s_mov_b64 s[0:1], -1
	global_store_dwordx4 v[150:151], v[124:127], off nt
	global_store_dwordx4 v[108:109], v[104:107], off nt
	global_store_dwordx4 v[92:93], v[88:91], off nt
	global_store_dwordx4 v[76:77], v[72:75], off nt
	global_store_dwordx4 v[76:77], v[68:71], off offset:256 nt
	global_store_dwordx4 v[56:57], v[60:63], off nt
	global_store_dwordx4 v[46:47], v[40:43], off nt
	global_store_dwordx4 v[30:31], v[24:27], off nt
	global_store_dwordx4 v[14:15], v[8:11], off nt
	global_store_dwordx4 v[12:13], v[4:7], off offset:256 nt
	s_cbranch_vccnz .LBB0_996
	s_andn2_b64 vcc, exec, s[6:7]
	s_cbranch_vccnz .LBB0_995
	s_barrier
	s_branch .LBB0_995
